# first K-tile of each w_in/GU unit: counted waits no longer wait for the previous epilogue's stores (vmcnt 16); phase entry drains its loads once
# speedup vs baseline: 1.0025x; 1.0025x over previous
.LBB0_157:
	s_and_b32 s27, s2, 3
	s_add_i32 m0, s46, 0x18000
	v_lshl_add_u64 v[0:1], v[0:1], 0, s[4:5]
	s_lshl_b32 s28, s26, 6
	s_lshl_b32 s29, s26, 13
	s_lshl_b32 s30, s27, 12
	s_waitcnt vmcnt(2)
	s_barrier
	global_load_lds_dwordx4 v[0:1], off
	s_add_i32 m0, s46, 0x1a000
	s_add_u32 s24, s42, 0x8000
	v_mov_b32_e32 v135, v209
	v_lshl_add_u64 v[0:1], v[2:3], 0, s[4:5]
	s_addc_u32 s25, s43, 0
	s_add_i32 s52, s46, 0x8000
	v_mov_b32_e32 v131, v209
	global_load_lds_dwordx4 v[0:1], off
	v_lshl_add_u64 v[0:1], s[24:25], 0, v[134:135]
	s_mov_b32 m0, s52
	s_add_i32 s53, s46, 0xa000
	global_load_lds_dwordx4 v[0:1], off
	v_lshl_add_u64 v[0:1], s[24:25], 0, v[130:131]
	s_add_u32 s24, s40, 0x10080
	s_mov_b32 m0, s53
	s_addc_u32 s25, s41, 0
	global_load_lds_dwordx4 v[0:1], off
	s_add_i32 m0, s46, 0x1c000
	v_lshl_add_u64 v[0:1], s[24:25], 0, v[132:133]
	global_load_lds_dwordx4 v[0:1], off
	v_lshl_add_u64 v[0:1], s[24:25], 0, v[128:129]
	s_add_i32 m0, s46, 0x1e000
	s_cmpk_lt_u32 s3, 0x100
	global_load_lds_dwordx4 v[0:1], off
	s_sext_i32_i8 s2, s0
	s_cselect_b64 s[24:25], -1, 0
	s_lshl_b32 s0, s26, 2
	s_or_b32 s0, s0, s27
	s_mulk_i32 s0, 0x900
	v_and_b32_e32 v1, 15, v4
	v_and_b32_e32 v2, 48, v4
	v_lshlrev_b32_e32 v3, 2, v4
	s_add_i32 s0, s0, 0
	v_lshl_or_b32 v0, v1, 6, v2
	v_and_b32_e32 v3, 32, v3
	s_add_i32 s0, s0, 0x20000
	v_bitop3_b32 v13, v0, s29, v3 bitop3:0xde
	v_bitop3_b32 v143, v0, s30, v3 bitop3:0xde
	s_waitcnt vmcnt(6)
	v_bfe_u32 v3, v4, 3, 3
	v_and_b32_e32 v0, 7, v4
	v_mov_b32_e32 v14, s0
	s_movk_i32 s0, 0x90
	v_or_b32_e32 v141, s28, v1
	v_lshlrev_b32_e32 v4, 4, v0
	v_or_b32_e32 v145, s28, v3
	s_lshl_b32 s3, s27, 6
	v_lshlrev_b32_e32 v0, 3, v0
	v_mad_u32_u24 v1, v1, s0, v14
	v_mad_u32_u24 v3, v3, s0, v14
	v_add3_u32 v9, v9, v11, v10
	v_add3_u32 v5, v5, v7, v6
	v_readlane_b32 s50, v254, 32
	v_or_b32_e32 v147, 16, v145
	v_or_b32_e32 v149, 32, v145
	v_or_b32_e32 v151, 48, v145
	s_ashr_i32 s56, s9, 31
	v_lshl_or_b32 v136, v9, 6, v12
	v_mov_b32_e32 v137, v209
	v_lshl_or_b32 v138, v5, 6, v8
	v_mov_b32_e32 v139, v209
	s_mov_b32 s57, 0
	v_mov_b32_e32 v140, 1.0
	v_add_u32_e32 v153, 0, v13
	v_add_u32_e32 v155, v1, v2
	v_add_u32_e32 v158, v3, v4
	s_lshl_b32 s0, s3, 1
	v_lshlrev_b32_e32 v208, 1, v0
	v_mov_b32_e32 v142, 1.0
	v_mov_b32_e32 v144, 1.0
	v_mov_b32_e32 v146, 1.0
	v_mov_b32_e32 v148, 1.0
	v_mov_b32_e32 v150, 1.0
	v_mov_b32_e32 v152, 1.0
	v_mov_b32_e32 v154, 1.0
	v_readlane_b32 s51, v254, 33
	s_waitcnt vmcnt(0)
	s_barrier
	s_branch .LBB0_160

.LBB0_162:
	s_ashr_i32 s29, s28, 31
	s_lshl_b64 s[30:31], s[28:29], 19
	s_add_u32 s30, s62, s30
	s_addc_u32 s31, s63, s31
	s_and_b64 s[34:35], s[36:37], exec
	s_cselect_b32 s29, s31, s43
	s_cselect_b32 s60, s30, s42
	s_ashr_i32 s27, s26, 31
	s_lshl_b64 s[34:35], s[26:27], 19
	s_add_u32 s34, s17, s34
	s_addc_u32 s35, s18, s35
	s_and_b64 s[44:45], s[36:37], exec
	s_cselect_b32 s27, s35, s41
	s_cselect_b32 s61, s34, s40
	s_lshl_b32 s3, s38, 8
	v_add_u32_e32 v0, s3, v141
	s_add_u32 s64, s40, 0x100
	v_ashrrev_i32_e32 v1, 31, v0
	s_addc_u32 s65, s41, 0
	v_lshl_add_u64 v[156:157], v[0:1], 2, s[72:73]
	s_add_u32 s38, s42, 0xa000
	v_mov_b32_e32 v0, 0
	s_addc_u32 s39, s43, 0
	s_mov_b32 s66, -2
	s_mov_b64 s[40:41], 0
	s_add_u32 s42, s38, 0x6000
	s_addc_u32 s43, s39, 0
	s_and_b64 s[40:41], s[40:41], exec
	s_cselect_b32 s44, s60, s42
	s_cselect_b32 s45, s29, s43
	s_cselect_b32 s43, s27, s65
	s_cselect_b32 s42, s61, s64
	s_add_u32 s40, s44, 0x8000
	s_addc_u32 s41, s45, 0
	s_add_i32 s67, 0, 0x10000
	v_add_u32_e32 v159, s67, v143
	s_add_i32 s70, 0, 0x14000
	ds_read_b128 v[160:163], v159
	ds_read_b128 v[164:167], v159 offset:1024
	ds_read_b128 v[168:171], v159 offset:2048
	ds_read_b128 v[172:175], v159 offset:3072
	v_add_u32_e32 v159, s70, v143
	ds_read_b128 v[176:179], v159
	ds_read_b128 v[180:183], v159 offset:1024
	ds_read_b128 v[184:187], v159 offset:2048
	ds_read_b128 v[188:191], v159 offset:3072
	s_add_i32 m0, s46, 0xc000
	ds_read_b128 v[192:195], v153
	ds_read_b128 v[196:199], v153 offset:1024
	ds_read_b128 v[200:203], v153 offset:2048
	ds_read_b128 v[204:207], v153 offset:3072
	ds_read_b128 v[218:221], v153 offset:4096
	ds_read_b128 v[222:225], v153 offset:5120
	ds_read_b128 v[226:229], v153 offset:6144
	ds_read_b128 v[230:233], v153 offset:7168
	global_load_lds_dwordx4 v136, s[38:39]
	s_add_i32 m0, s46, 0xe000
	s_nop 0
	global_load_lds_dwordx4 v138, s[38:39]
	s_waitcnt vmcnt(16)
	s_waitcnt lgkmcnt(0)
	s_barrier
	s_setprio 1
	s_waitcnt lgkmcnt(0)
	v_mfma_f32_16x16x32_bf16 v[124:127], v[160:163], v[192:195], 0
	v_mfma_f32_16x16x32_bf16 v[120:123], v[168:171], v[192:195], 0
	v_mfma_f32_16x16x32_bf16 v[108:111], v[160:163], v[200:203], 0
	v_mfma_f32_16x16x32_bf16 v[104:107], v[168:171], v[200:203], 0
	v_mfma_f32_16x16x32_bf16 v[92:95], v[160:163], v[218:221], 0
	v_mfma_f32_16x16x32_bf16 v[88:91], v[168:171], v[218:221], 0
	v_mfma_f32_16x16x32_bf16 v[76:79], v[160:163], v[226:229], 0
	v_mfma_f32_16x16x32_bf16 v[72:75], v[168:171], v[226:229], 0
	v_mfma_f32_16x16x32_bf16 v[124:127], v[164:167], v[196:199], v[124:127]
	v_mfma_f32_16x16x32_bf16 v[120:123], v[172:175], v[196:199], v[120:123]
	v_mfma_f32_16x16x32_bf16 v[108:111], v[164:167], v[204:207], v[108:111]
	v_mfma_f32_16x16x32_bf16 v[104:107], v[172:175], v[204:207], v[104:107]
	v_mfma_f32_16x16x32_bf16 v[92:95], v[164:167], v[222:225], v[92:95]
	v_mfma_f32_16x16x32_bf16 v[88:91], v[172:175], v[222:225], v[88:91]
	v_mfma_f32_16x16x32_bf16 v[76:79], v[164:167], v[230:233], v[76:79]
	v_mfma_f32_16x16x32_bf16 v[72:75], v[172:175], v[230:233], v[72:75]
	s_setprio 0
	s_setprio 1
	v_mfma_f32_16x16x32_bf16 v[116:119], v[176:179], v[192:195], 0
	v_mfma_f32_16x16x32_bf16 v[112:115], v[184:187], v[192:195], 0
	v_mfma_f32_16x16x32_bf16 v[100:103], v[176:179], v[200:203], 0
	v_mfma_f32_16x16x32_bf16 v[96:99], v[184:187], v[200:203], 0
	v_mfma_f32_16x16x32_bf16 v[84:87], v[176:179], v[218:221], 0
	v_mfma_f32_16x16x32_bf16 v[80:83], v[184:187], v[218:221], 0
	v_mfma_f32_16x16x32_bf16 v[68:71], v[176:179], v[226:229], 0
	v_mfma_f32_16x16x32_bf16 v[64:67], v[184:187], v[226:229], 0
	v_mfma_f32_16x16x32_bf16 v[116:119], v[180:183], v[196:199], v[116:119]
	v_mfma_f32_16x16x32_bf16 v[112:115], v[188:191], v[196:199], v[112:115]
	v_mfma_f32_16x16x32_bf16 v[100:103], v[180:183], v[204:207], v[100:103]
	v_mfma_f32_16x16x32_bf16 v[96:99], v[188:191], v[204:207], v[96:99]
	v_mfma_f32_16x16x32_bf16 v[84:87], v[180:183], v[222:225], v[84:87]
	v_mfma_f32_16x16x32_bf16 v[80:83], v[188:191], v[222:225], v[80:83]
	v_mfma_f32_16x16x32_bf16 v[68:71], v[180:183], v[230:233], v[68:71]
	v_mfma_f32_16x16x32_bf16 v[64:67], v[188:191], v[230:233], v[64:67]
	s_setprio 0
	s_barrier
	s_add_i32 s67, s67, s19
	s_mov_b32 m0, s67
	ds_read_b128 v[192:195], v153 offset:16384
	ds_read_b128 v[196:199], v153 offset:17408
	ds_read_b128 v[200:203], v153 offset:18432
	ds_read_b128 v[204:207], v153 offset:19456
	ds_read_b128 v[218:221], v153 offset:20480
	ds_read_b128 v[222:225], v153 offset:21504
	ds_read_b128 v[226:229], v153 offset:22528
	ds_read_b128 v[230:233], v153 offset:23552
	global_load_lds_dwordx4 v132, s[42:43]
	s_add_i32 m0, s67, 0x2000
	s_add_u32 s68, s42, 0x10000
	s_addc_u32 s69, s43, 0
	s_add_i32 s67, s70, s19
	global_load_lds_dwordx4 v128, s[42:43]
	s_mov_b32 m0, s67
	s_nop 0
	global_load_lds_dwordx4 v132, s[68:69]
	s_add_i32 m0, s67, 0x2000
	s_nop 0
	global_load_lds_dwordx4 v128, s[68:69]
	s_mov_b32 m0, s46
	s_nop 0
	global_load_lds_dwordx4 v134, s[44:45]
	s_mov_b32 m0, s47
	s_nop 0
	global_load_lds_dwordx4 v130, s[44:45]
	s_waitcnt vmcnt(16)
	s_waitcnt lgkmcnt(0)
	s_barrier
	s_setprio 1
	s_waitcnt lgkmcnt(0)
	v_mfma_f32_16x16x32_bf16 v[60:63], v[160:163], v[192:195], 0
	v_mfma_f32_16x16x32_bf16 v[56:59], v[168:171], v[192:195], 0
	v_mfma_f32_16x16x32_bf16 v[44:47], v[160:163], v[200:203], 0
	v_mfma_f32_16x16x32_bf16 v[40:43], v[168:171], v[200:203], 0
	v_mfma_f32_16x16x32_bf16 v[28:31], v[160:163], v[218:221], 0
	v_mfma_f32_16x16x32_bf16 v[24:27], v[168:171], v[218:221], 0
	v_mfma_f32_16x16x32_bf16 v[12:15], v[160:163], v[226:229], 0
	v_mfma_f32_16x16x32_bf16 v[8:11], v[168:171], v[226:229], 0
	v_mfma_f32_16x16x32_bf16 v[60:63], v[164:167], v[196:199], v[60:63]
	v_mfma_f32_16x16x32_bf16 v[56:59], v[172:175], v[196:199], v[56:59]
	v_mfma_f32_16x16x32_bf16 v[44:47], v[164:167], v[204:207], v[44:47]
	v_mfma_f32_16x16x32_bf16 v[40:43], v[172:175], v[204:207], v[40:43]
	v_mfma_f32_16x16x32_bf16 v[28:31], v[164:167], v[222:225], v[28:31]
	v_mfma_f32_16x16x32_bf16 v[24:27], v[172:175], v[222:225], v[24:27]
	v_mfma_f32_16x16x32_bf16 v[12:15], v[164:167], v[230:233], v[12:15]
	v_mfma_f32_16x16x32_bf16 v[8:11], v[172:175], v[230:233], v[8:11]
	s_setprio 0
	s_setprio 1
	v_mfma_f32_16x16x32_bf16 v[52:55], v[176:179], v[192:195], 0
	v_mfma_f32_16x16x32_bf16 v[48:51], v[184:187], v[192:195], 0
	v_mfma_f32_16x16x32_bf16 v[36:39], v[176:179], v[200:203], 0
	v_mfma_f32_16x16x32_bf16 v[32:35], v[184:187], v[200:203], 0
	v_mfma_f32_16x16x32_bf16 v[20:23], v[176:179], v[218:221], 0
	v_mfma_f32_16x16x32_bf16 v[16:19], v[184:187], v[218:221], 0
	v_mfma_f32_16x16x32_bf16 v[4:7], v[176:179], v[226:229], 0
	v_mfma_f32_16x16x32_bf16 v[0:3], v[184:187], v[226:229], 0
	v_mfma_f32_16x16x32_bf16 v[52:55], v[180:183], v[196:199], v[52:55]
	v_mfma_f32_16x16x32_bf16 v[48:51], v[188:191], v[196:199], v[48:51]
	v_mfma_f32_16x16x32_bf16 v[36:39], v[180:183], v[204:207], v[36:39]
	v_mfma_f32_16x16x32_bf16 v[32:35], v[188:191], v[204:207], v[32:35]
	v_mfma_f32_16x16x32_bf16 v[20:23], v[180:183], v[222:225], v[20:23]
	v_mfma_f32_16x16x32_bf16 v[16:19], v[188:191], v[222:225], v[16:19]
	v_mfma_f32_16x16x32_bf16 v[4:7], v[180:183], v[230:233], v[4:7]
	v_mfma_f32_16x16x32_bf16 v[0:3], v[188:191], v[230:233], v[0:3]
	s_setprio 0
	s_barrier
	s_branch .Lwin_mid

.LBB0_565:
	v_lshrrev_b32_e32 v14, 1, v12
	v_and_b32_e32 v14, 24, v14
	v_and_b32_e32 v13, 15, v12
	v_lshlrev_b32_e32 v15, 1, v14
	v_lshlrev_b32_e32 v12, 2, v12
	s_sext_i32_i16 s2, s0
	s_and_b32 s26, s25, 3
	v_lshl_or_b32 v158, s24, 6, v13
	v_lshl_or_b32 v13, v13, 6, v15
	s_lshl_b32 s0, s24, 13
	v_and_b32_e32 v12, 32, v12
	s_add_i32 m0, s48, 0x18000
	v_lshl_add_u64 v[0:1], v[0:1], 0, s[4:5]
	v_bitop3_b32 v15, v13, s0, v12 bitop3:0xde
	s_lshl_b32 s0, s26, 12
	s_waitcnt vmcnt(2)
	s_barrier
	global_load_lds_dwordx4 v[0:1], off
	s_add_i32 m0, s48, 0x1a000
	s_add_u32 s24, s42, 0x8000
	v_mov_b32_e32 v135, v209
	v_bitop3_b32 v159, v13, s0, v12 bitop3:0xde
	v_lshl_add_u64 v[0:1], v[2:3], 0, s[4:5]
	s_addc_u32 s25, s43, 0
	s_add_i32 s0, s48, 0x8000
	v_mov_b32_e32 v131, v209
	global_load_lds_dwordx4 v[0:1], off
	v_lshl_add_u64 v[0:1], s[24:25], 0, v[134:135]
	s_mov_b32 m0, s0
	s_add_i32 s56, s48, 0xa000
	global_load_lds_dwordx4 v[0:1], off
	v_lshl_add_u64 v[0:1], s[24:25], 0, v[130:131]
	s_add_u32 s24, s40, 0x40080
	s_mov_b32 m0, s56
	s_addc_u32 s25, s41, 0
	global_load_lds_dwordx4 v[0:1], off
	s_add_i32 m0, s48, 0x1c000
	v_lshl_add_u64 v[0:1], s[24:25], 0, v[132:133]
	global_load_lds_dwordx4 v[0:1], off
	v_lshl_add_u64 v[0:1], s[24:25], 0, v[128:129]
	s_add_i32 m0, s48, 0x1e000
	s_cmpk_lt_u32 s3, 0x100
	global_load_lds_dwordx4 v[0:1], off
	v_lshl_add_u32 v0, s26, 8, v158
	v_or_b32_e32 v2, 16, v0
	v_ashrrev_i32_e32 v1, 31, v0
	v_ashrrev_i32_e32 v3, 31, v2
	v_lshlrev_b64 v[136:137], 6, v[0:1]
	v_lshlrev_b64 v[138:139], 6, v[2:3]
	v_or_b32_e32 v2, 32, v0
	v_or_b32_e32 v0, 48, v0
	s_mov_b64 s[26:27], 0x2000
	v_ashrrev_i32_e32 v1, 31, v0
	v_lshl_add_u64 v[144:145], v[136:137], 0, s[26:27]
	s_mov_b64 s[26:27], 0x2400
	s_waitcnt vmcnt(6)
	v_lshlrev_b64 v[142:143], 6, v[0:1]
	v_lshl_add_u64 v[146:147], v[136:137], 0, s[26:27]
	s_mov_b64 s[26:27], 0x2800
	v_add3_u32 v0, v8, v10, v9
	v_ashrrev_i32_e32 v3, 31, v2
	v_lshl_add_u64 v[148:149], v[136:137], 0, s[26:27]
	s_mov_b64 s[26:27], 0x2c00
	v_lshl_or_b32 v152, v0, 6, v11
	v_add3_u32 v0, v4, v6, v5
	s_cselect_b64 s[24:25], -1, 0
	v_lshlrev_b64 v[140:141], 6, v[2:3]
	v_lshl_add_u64 v[150:151], v[136:137], 0, s[26:27]
	s_ashr_i32 s57, s9, 31
	v_mov_b32_e32 v153, v209
	v_lshl_or_b32 v154, v0, 6, v7
	v_mov_b32_e32 v155, v209
	s_mov_b32 s60, 0
	v_mov_b32_e32 v161, 1.0
	v_add_u32_e32 v160, 0, v15
	v_lshlrev_b32_e32 v208, 1, v14
	v_mov_b32_e32 v162, 1.0
	v_mov_b32_e32 v163, 1.0
	v_mov_b32_e32 v164, 1.0
	v_mov_b32_e32 v165, 1.0
	v_mov_b32_e32 v166, 1.0
	v_mov_b32_e32 v167, 1.0
	v_mov_b32_e32 v168, 1.0
	s_waitcnt vmcnt(0)
	s_barrier
	s_branch .LBB0_568

.LBB0_570:
	s_ashr_i32 s29, s28, 31
	s_lshl_b64 s[30:31], s[28:29], 19
	s_add_u32 s30, s62, s30
	s_addc_u32 s31, s63, s31
	s_and_b64 s[34:35], s[36:37], exec
	s_cselect_b32 s3, s31, s43
	s_cselect_b32 s29, s30, s42
	s_ashr_i32 s27, s26, 31
	s_lshl_b64 s[34:35], s[26:27], 19
	s_add_u32 s34, s17, s34
	s_addc_u32 s35, s18, s35
	s_and_b64 s[44:45], s[36:37], exec
	s_cselect_b32 s27, s35, s41
	s_cselect_b32 s39, s34, s40
	s_add_u32 s61, s40, 0x100
	v_lshl_add_u32 v0, s38, 8, v158
	s_addc_u32 s64, s41, 0
	v_ashrrev_i32_e32 v1, 31, v0
	s_add_u32 s40, s42, 0xa000
	v_mov_b32_e32 v8, 0
	v_lshl_add_u64 v[156:157], v[0:1], 2, s[72:73]
	s_addc_u32 s41, s43, 0
	s_mov_b32 s65, -2
	s_mov_b64 s[42:43], 0
	s_add_u32 s44, s40, 0x6000
	s_addc_u32 s45, s41, 0
	s_and_b64 s[42:43], s[42:43], exec
	s_cselect_b32 s46, s29, s44
	s_cselect_b32 s47, s3, s45
	s_cselect_b32 s45, s27, s64
	s_cselect_b32 s44, s39, s61
	s_add_u32 s42, s46, 0x8000
	s_addc_u32 s43, s47, 0
	s_add_i32 s66, 0, 0x10000
	v_add_u32_e32 v169, s66, v159
	s_add_i32 s68, 0, 0x14000
	ds_read_b128 v[170:173], v169
	ds_read_b128 v[174:177], v169 offset:1024
	ds_read_b128 v[178:181], v169 offset:2048
	ds_read_b128 v[182:185], v169 offset:3072
	v_add_u32_e32 v169, s68, v159
	ds_read_b128 v[186:189], v169
	ds_read_b128 v[190:193], v169 offset:1024
	ds_read_b128 v[194:197], v169 offset:2048
	ds_read_b128 v[198:201], v169 offset:3072
	s_add_i32 m0, s48, 0xc000
	ds_read_b128 v[202:205], v160
	ds_read_b128 v[218:221], v160 offset:1024
	ds_read_b128 v[222:225], v160 offset:2048
	ds_read_b128 v[226:229], v160 offset:3072
	ds_read_b128 v[230:233], v160 offset:4096
	ds_read_b128 v[234:237], v160 offset:5120
	ds_read_b128 v[238:241], v160 offset:6144
	ds_read_b128 v[246:249], v160 offset:7168
	global_load_lds_dwordx4 v152, s[40:41]
	s_add_i32 m0, s48, 0xe000
	s_nop 0
	global_load_lds_dwordx4 v154, s[40:41]
	s_waitcnt vmcnt(16)
	s_waitcnt lgkmcnt(0)
	s_barrier
	s_setprio 1
	s_waitcnt lgkmcnt(0)
	v_mfma_f32_16x16x32_bf16 v[116:119], v[170:173], v[202:205], 0
	v_mfma_f32_16x16x32_bf16 v[124:127], v[178:181], v[202:205], 0
	v_mfma_f32_16x16x32_bf16 v[100:103], v[170:173], v[222:225], 0
	v_mfma_f32_16x16x32_bf16 v[108:111], v[178:181], v[222:225], 0
	v_mfma_f32_16x16x32_bf16 v[84:87], v[170:173], v[230:233], 0
	v_mfma_f32_16x16x32_bf16 v[92:95], v[178:181], v[230:233], 0
	v_mfma_f32_16x16x32_bf16 v[68:71], v[170:173], v[238:241], 0
	v_mfma_f32_16x16x32_bf16 v[76:79], v[178:181], v[238:241], 0
	v_mfma_f32_16x16x32_bf16 v[116:119], v[174:177], v[218:221], v[116:119]
	v_mfma_f32_16x16x32_bf16 v[124:127], v[182:185], v[218:221], v[124:127]
	v_mfma_f32_16x16x32_bf16 v[100:103], v[174:177], v[226:229], v[100:103]
	v_mfma_f32_16x16x32_bf16 v[108:111], v[182:185], v[226:229], v[108:111]
	v_mfma_f32_16x16x32_bf16 v[84:87], v[174:177], v[234:237], v[84:87]
	v_mfma_f32_16x16x32_bf16 v[92:95], v[182:185], v[234:237], v[92:95]
	v_mfma_f32_16x16x32_bf16 v[68:71], v[174:177], v[246:249], v[68:71]
	v_mfma_f32_16x16x32_bf16 v[76:79], v[182:185], v[246:249], v[76:79]
	s_setprio 0
	s_setprio 1
	v_mfma_f32_16x16x32_bf16 v[112:115], v[186:189], v[202:205], 0
	v_mfma_f32_16x16x32_bf16 v[120:123], v[194:197], v[202:205], 0
	v_mfma_f32_16x16x32_bf16 v[96:99], v[186:189], v[222:225], 0
	v_mfma_f32_16x16x32_bf16 v[104:107], v[194:197], v[222:225], 0
	v_mfma_f32_16x16x32_bf16 v[80:83], v[186:189], v[230:233], 0
	v_mfma_f32_16x16x32_bf16 v[88:91], v[194:197], v[230:233], 0
	v_mfma_f32_16x16x32_bf16 v[64:67], v[186:189], v[238:241], 0
	v_mfma_f32_16x16x32_bf16 v[72:75], v[194:197], v[238:241], 0
	v_mfma_f32_16x16x32_bf16 v[112:115], v[190:193], v[218:221], v[112:115]
	v_mfma_f32_16x16x32_bf16 v[120:123], v[198:201], v[218:221], v[120:123]
	v_mfma_f32_16x16x32_bf16 v[96:99], v[190:193], v[226:229], v[96:99]
	v_mfma_f32_16x16x32_bf16 v[104:107], v[198:201], v[226:229], v[104:107]
	v_mfma_f32_16x16x32_bf16 v[80:83], v[190:193], v[234:237], v[80:83]
	v_mfma_f32_16x16x32_bf16 v[88:91], v[198:201], v[234:237], v[88:91]
	v_mfma_f32_16x16x32_bf16 v[64:67], v[190:193], v[246:249], v[64:67]
	v_mfma_f32_16x16x32_bf16 v[72:75], v[198:201], v[246:249], v[72:75]
	s_setprio 0
	s_barrier
	s_add_i32 s66, s66, s19
	s_mov_b32 m0, s66
	ds_read_b128 v[202:205], v160 offset:16384
	ds_read_b128 v[218:221], v160 offset:17408
	ds_read_b128 v[222:225], v160 offset:18432
	ds_read_b128 v[226:229], v160 offset:19456
	ds_read_b128 v[230:233], v160 offset:20480
	ds_read_b128 v[234:237], v160 offset:21504
	ds_read_b128 v[238:241], v160 offset:22528
	ds_read_b128 v[246:249], v160 offset:23552
	global_load_lds_dwordx4 v132, s[44:45]
	s_add_i32 m0, s66, 0x2000
	s_add_u32 s66, s44, 0x40000
	s_addc_u32 s67, s45, 0
	s_add_i32 s68, s68, s19
	global_load_lds_dwordx4 v128, s[44:45]
	s_mov_b32 m0, s68
	s_nop 0
	global_load_lds_dwordx4 v132, s[66:67]
	s_add_i32 m0, s68, 0x2000
	s_nop 0
	global_load_lds_dwordx4 v128, s[66:67]
	s_mov_b32 m0, s48
	s_nop 0
	global_load_lds_dwordx4 v134, s[46:47]
	s_mov_b32 m0, s49
	s_nop 0
	global_load_lds_dwordx4 v130, s[46:47]
	s_waitcnt vmcnt(16)
	s_waitcnt lgkmcnt(0)
	s_barrier
	s_setprio 1
	s_waitcnt lgkmcnt(0)
	v_mfma_f32_16x16x32_bf16 v[52:55], v[170:173], v[202:205], 0
	v_mfma_f32_16x16x32_bf16 v[60:63], v[178:181], v[202:205], 0
	v_mfma_f32_16x16x32_bf16 v[36:39], v[170:173], v[222:225], 0
	v_mfma_f32_16x16x32_bf16 v[44:47], v[178:181], v[222:225], 0
	v_mfma_f32_16x16x32_bf16 v[20:23], v[170:173], v[230:233], 0
	v_mfma_f32_16x16x32_bf16 v[28:31], v[178:181], v[230:233], 0
	v_mfma_f32_16x16x32_bf16 v[4:7], v[170:173], v[238:241], 0
	v_mfma_f32_16x16x32_bf16 v[12:15], v[178:181], v[238:241], 0
	v_mfma_f32_16x16x32_bf16 v[52:55], v[174:177], v[218:221], v[52:55]
	v_mfma_f32_16x16x32_bf16 v[60:63], v[182:185], v[218:221], v[60:63]
	v_mfma_f32_16x16x32_bf16 v[36:39], v[174:177], v[226:229], v[36:39]
	v_mfma_f32_16x16x32_bf16 v[44:47], v[182:185], v[226:229], v[44:47]
	v_mfma_f32_16x16x32_bf16 v[20:23], v[174:177], v[234:237], v[20:23]
	v_mfma_f32_16x16x32_bf16 v[28:31], v[182:185], v[234:237], v[28:31]
	v_mfma_f32_16x16x32_bf16 v[4:7], v[174:177], v[246:249], v[4:7]
	v_mfma_f32_16x16x32_bf16 v[12:15], v[182:185], v[246:249], v[12:15]
	s_setprio 0
	s_setprio 1
	v_mfma_f32_16x16x32_bf16 v[48:51], v[186:189], v[202:205], 0
	v_mfma_f32_16x16x32_bf16 v[56:59], v[194:197], v[202:205], 0
	v_mfma_f32_16x16x32_bf16 v[32:35], v[186:189], v[222:225], 0
	v_mfma_f32_16x16x32_bf16 v[40:43], v[194:197], v[222:225], 0
	v_mfma_f32_16x16x32_bf16 v[16:19], v[186:189], v[230:233], 0
	v_mfma_f32_16x16x32_bf16 v[24:27], v[194:197], v[230:233], 0
	v_mfma_f32_16x16x32_bf16 v[0:3], v[186:189], v[238:241], 0
	v_mfma_f32_16x16x32_bf16 v[8:11], v[194:197], v[238:241], 0
	v_mfma_f32_16x16x32_bf16 v[48:51], v[190:193], v[218:221], v[48:51]
	v_mfma_f32_16x16x32_bf16 v[56:59], v[198:201], v[218:221], v[56:59]
	v_mfma_f32_16x16x32_bf16 v[32:35], v[190:193], v[226:229], v[32:35]
	v_mfma_f32_16x16x32_bf16 v[40:43], v[198:201], v[226:229], v[40:43]
	v_mfma_f32_16x16x32_bf16 v[16:19], v[190:193], v[234:237], v[16:19]
	v_mfma_f32_16x16x32_bf16 v[24:27], v[198:201], v[234:237], v[24:27]
	v_mfma_f32_16x16x32_bf16 v[0:3], v[190:193], v[246:249], v[0:3]
	v_mfma_f32_16x16x32_bf16 v[8:11], v[198:201], v[246:249], v[8:11]
	s_setprio 0
	s_barrier
	s_branch .Lgu_mid
